# P1 tail: workgroups that ran the last-round tile also convert the last 2048 weight items (2 per wave); the others stop at item 9984
# baseline (speedup 1.0000x reference)
; #define LAS __attribute__((address_space(3)))
; __device__ __forceinline__ unsigned pk2(float lo, float hi) { return cvtpk_(lo, hi); }
; #define INF(k) ((const float*)LDP(k))
; __global__ void __launch_bounds__(512, 2) fwd_megakernel(Args a) {
;     ...
;         const int rem = ((T / 256) * (INW / 256)) % G;
;         if (rem == 0 || bid >= rem) { PH_IDS (void)gw;
;             LAS float* scr = (LAS float*)(lds + wave * 16384);
;             const int first = (rem == 0 ? bid : bid - rem) * 8 + wave, step = (rem == 0 ? G : G - rem) * 8;
;             {
;                 const int gt2 = (rem == 0 ? bid : bid - rem) * 512 + tid, ngt2 = (rem == 0 ? G : G - rem) * 512;
;                 for (int i = gt2; i < T * 64; i += ngt2) { const f32x4 v = ((const f32x4*)INF(I_P))[i]; u32x2 w; w.x = pk2(v[0], v[1]); w.y = pk2(v[2], v[3]); ((u32x2*)PB)[i] = w; }
;             }
.LBB0_132:
	s_add_u32 s62, s52, 0x5b00000
	s_addc_u32 s63, s53, 0
	s_add_u32 s70, s52, 0x100000
	s_addc_u32 s71, s53, 0
	s_add_u32 s60, s52, 0x5300000
	s_addc_u32 s61, s53, 0
	s_add_u32 s68, s52, 0x900000
	s_addc_u32 s69, s53, 0
	s_add_u32 s66, s52, 0x3d00000
	s_addc_u32 s67, s53, 0
	s_abs_i32 s0, s54
	v_cvt_f32_u32_e32 v0, s0
	s_sub_i32 s1, 0, s0
	v_rcp_iflag_f32_e32 v0, v0
	s_nop 0
	v_mul_f32_e32 v0, 0x4f7ffffe, v0
	v_cvt_u32_f32_e32 v0, v0
	s_nop 0
	v_readfirstlane_b32 s2, v0
	s_mul_i32 s1, s1, s2
	s_mul_hi_u32 s1, s2, s1
	s_add_i32 s2, s2, s1
	s_mul_hi_u32 s1, s2, 0x980
	s_mul_i32 s1, s1, s0
	s_sub_i32 s1, 0x980, s1
	s_sub_i32 s2, s1, s0
	s_cmp_ge_u32 s1, s0
	s_cselect_b32 s1, s2, s1
	s_sub_i32 s2, s1, s0
	s_cmp_ge_u32 s1, s0
	s_cselect_b32 s0, s2, s1
	s_cmp_lg_u32 s0, 0
	s_cselect_b64 s[2:3], -1, 0
	s_cmp_lt_i32 s33, s0
	s_cselect_b64 s[4:5], -1, 0
	s_and_b64 s[2:3], s[2:3], s[4:5]
	s_and_b64 vcc, exec, s[2:3]
	s_cbranch_vccz .Ltail_conv_wg
	v_mbcnt_lo_u32_b32 v0, -1, 0
	v_mbcnt_hi_u32_b32 v0, -1, v0
	s_mov_b32 s2, s33
	v_add_u32_e32 v8, s84, v0
	s_mov_b32 s12, s0
	s_movk_i32 s94, 0x2700
	s_movk_i32 s95, 0x2f00
	s_nop 0
	v_readfirstlane_b32 s3, v8
	s_mov_b64 s[0:1], exec
	s_branch .LBB0_136
.Ltail_conv_wg:
	s_mov_b32 s94, 0
	s_cmp_lg_u32 s0, 0
	s_movk_i32 s95, 0x2f00
	s_cselect_b32 s95, 0x2700, s95
	v_mbcnt_lo_u32_b32 v0, -1, 0
	v_mbcnt_hi_u32_b32 v0, -1, v0
	s_sub_i32 s2, s33, s0
	v_add_u32_e32 v8, s84, v0
	s_sub_i32 s12, s54, s0
	v_lshl_add_u32 v0, s2, 9, v8
	s_mov_b32 s0, 0x100000
	v_readfirstlane_b32 s3, v8
	v_cmp_gt_i32_e32 vcc, s0, v0
	s_and_saveexec_b64 s[0:1], vcc
	s_cbranch_execz .LBB0_136
	s_add_i32 s5, 0, 0x23c48
	v_mov_b32_e32 v1, s5
	ds_read_b64 v[2:3], v1
	s_lshl_b32 s4, s12, 9
	v_ashrrev_i32_e32 v1, 31, v0
	s_ashr_i32 s5, s4, 31
	v_lshl_add_u64 v[6:7], v[0:1], 3, s[52:53]
	s_mov_b64 s[8:9], 0x9c00000
	v_lshlrev_b64 v[4:5], 4, v[0:1]
	s_lshl_b64 s[6:7], s[4:5], 4
	v_lshl_add_u64 v[6:7], v[6:7], 0, s[8:9]
	s_lshl_b64 s[8:9], s[4:5], 3
	s_mov_b64 s[10:11], 0
	s_mov_b32 s5, 0xfffff
	s_cmp_eq_u32 s4, 0x10000
	s_cbranch_scc0 .LBB0_135
	s_waitcnt lgkmcnt(0)
	v_readfirstlane_b32 s15, v3
	v_readfirstlane_b32 s14, v2
	s_nop 1
	v_lshl_add_u64 v[88:89], s[14:15], 0, v[4:5]
	global_load_dwordx4 v[92:95], v[88:89], off
	v_lshl_add_u64 v[88:89], v[88:89], 0, s[6:7]
	global_load_dwordx4 v[96:99], v[88:89], off
	v_lshl_add_u64 v[88:89], v[88:89], 0, s[6:7]
	global_load_dwordx4 v[100:103], v[88:89], off
	v_lshl_add_u64 v[88:89], v[88:89], 0, s[6:7]
	global_load_dwordx4 v[104:107], v[88:89], off
	v_lshl_add_u64 v[88:89], v[88:89], 0, s[6:7]
	global_load_dwordx4 v[108:111], v[88:89], off
	v_lshl_add_u64 v[88:89], v[88:89], 0, s[6:7]
	global_load_dwordx4 v[112:115], v[88:89], off
	v_lshl_add_u64 v[88:89], v[88:89], 0, s[6:7]
	global_load_dwordx4 v[116:119], v[88:89], off
	v_lshl_add_u64 v[88:89], v[88:89], 0, s[6:7]
	global_load_dwordx4 v[120:123], v[88:89], off
	v_lshl_add_u64 v[88:89], v[88:89], 0, s[6:7]
	global_load_dwordx4 v[124:127], v[88:89], off
	v_lshl_add_u64 v[88:89], v[88:89], 0, s[6:7]
	global_load_dwordx4 v[128:131], v[88:89], off
	v_lshl_add_u64 v[88:89], v[88:89], 0, s[6:7]
	global_load_dwordx4 v[132:135], v[88:89], off
	v_lshl_add_u64 v[88:89], v[88:89], 0, s[6:7]
	global_load_dwordx4 v[136:139], v[88:89], off
	v_lshl_add_u64 v[88:89], v[88:89], 0, s[6:7]
	global_load_dwordx4 v[140:143], v[88:89], off
	v_lshl_add_u64 v[88:89], v[88:89], 0, s[6:7]
	global_load_dwordx4 v[144:147], v[88:89], off
	v_lshl_add_u64 v[88:89], v[88:89], 0, s[6:7]
	global_load_dwordx4 v[148:151], v[88:89], off
	v_lshl_add_u64 v[88:89], v[88:89], 0, s[6:7]
	global_load_dwordx4 v[152:155], v[88:89], off
	s_waitcnt vmcnt(15)
	v_cvt_pk_bf16_f32 v92, v92, v93
	v_cvt_pk_bf16_f32 v93, v94, v95
	global_store_dwordx2 v[6:7], v[92:93], off
	v_lshl_add_u64 v[6:7], v[6:7], 0, s[8:9]
	s_waitcnt vmcnt(15)
	v_cvt_pk_bf16_f32 v96, v96, v97
	v_cvt_pk_bf16_f32 v97, v98, v99
	global_store_dwordx2 v[6:7], v[96:97], off
	v_lshl_add_u64 v[6:7], v[6:7], 0, s[8:9]
	s_waitcnt vmcnt(15)
	v_cvt_pk_bf16_f32 v100, v100, v101
	v_cvt_pk_bf16_f32 v101, v102, v103
	global_store_dwordx2 v[6:7], v[100:101], off
	v_lshl_add_u64 v[6:7], v[6:7], 0, s[8:9]
	s_waitcnt vmcnt(15)
	v_cvt_pk_bf16_f32 v104, v104, v105
	v_cvt_pk_bf16_f32 v105, v106, v107
	global_store_dwordx2 v[6:7], v[104:105], off
	v_lshl_add_u64 v[6:7], v[6:7], 0, s[8:9]
	s_waitcnt vmcnt(15)
	v_cvt_pk_bf16_f32 v108, v108, v109
	v_cvt_pk_bf16_f32 v109, v110, v111
	global_store_dwordx2 v[6:7], v[108:109], off
	v_lshl_add_u64 v[6:7], v[6:7], 0, s[8:9]
	s_waitcnt vmcnt(15)
	v_cvt_pk_bf16_f32 v112, v112, v113
	v_cvt_pk_bf16_f32 v113, v114, v115
	global_store_dwordx2 v[6:7], v[112:113], off
	v_lshl_add_u64 v[6:7], v[6:7], 0, s[8:9]
	s_waitcnt vmcnt(15)
	v_cvt_pk_bf16_f32 v116, v116, v117
	v_cvt_pk_bf16_f32 v117, v118, v119
	global_store_dwordx2 v[6:7], v[116:117], off
	v_lshl_add_u64 v[6:7], v[6:7], 0, s[8:9]
	s_waitcnt vmcnt(15)
	v_cvt_pk_bf16_f32 v120, v120, v121
	v_cvt_pk_bf16_f32 v121, v122, v123
	global_store_dwordx2 v[6:7], v[120:121], off
	v_lshl_add_u64 v[6:7], v[6:7], 0, s[8:9]
	s_waitcnt vmcnt(15)
	v_cvt_pk_bf16_f32 v124, v124, v125
	v_cvt_pk_bf16_f32 v125, v126, v127
	global_store_dwordx2 v[6:7], v[124:125], off
	v_lshl_add_u64 v[6:7], v[6:7], 0, s[8:9]
	s_waitcnt vmcnt(15)
	v_cvt_pk_bf16_f32 v128, v128, v129
	v_cvt_pk_bf16_f32 v129, v130, v131
	global_store_dwordx2 v[6:7], v[128:129], off
	v_lshl_add_u64 v[6:7], v[6:7], 0, s[8:9]
	s_waitcnt vmcnt(15)
	v_cvt_pk_bf16_f32 v132, v132, v133
	v_cvt_pk_bf16_f32 v133, v134, v135
	global_store_dwordx2 v[6:7], v[132:133], off
	v_lshl_add_u64 v[6:7], v[6:7], 0, s[8:9]
	s_waitcnt vmcnt(15)
	v_cvt_pk_bf16_f32 v136, v136, v137
	v_cvt_pk_bf16_f32 v137, v138, v139
	global_store_dwordx2 v[6:7], v[136:137], off
	v_lshl_add_u64 v[6:7], v[6:7], 0, s[8:9]
	s_waitcnt vmcnt(15)
	v_cvt_pk_bf16_f32 v140, v140, v141
	v_cvt_pk_bf16_f32 v141, v142, v143
	global_store_dwordx2 v[6:7], v[140:141], off
	v_lshl_add_u64 v[6:7], v[6:7], 0, s[8:9]
	s_waitcnt vmcnt(15)
	v_cvt_pk_bf16_f32 v144, v144, v145
	v_cvt_pk_bf16_f32 v145, v146, v147
	global_store_dwordx2 v[6:7], v[144:145], off
	v_lshl_add_u64 v[6:7], v[6:7], 0, s[8:9]
	s_waitcnt vmcnt(15)
	v_cvt_pk_bf16_f32 v148, v148, v149
	v_cvt_pk_bf16_f32 v149, v150, v151
	global_store_dwordx2 v[6:7], v[148:149], off
	v_lshl_add_u64 v[6:7], v[6:7], 0, s[8:9]
	s_waitcnt vmcnt(15)
	v_cvt_pk_bf16_f32 v152, v152, v153
	v_cvt_pk_bf16_f32 v153, v154, v155
	global_store_dwordx2 v[6:7], v[152:153], off
	s_branch .LBB0_136

; __device__ __forceinline__ unsigned pk2(float lo, float hi) { return cvtpk_(lo, hi); }
; #define INF(k) ((const float*)LDP(k))
; __global__ void __launch_bounds__(512, 2) fwd_megakernel(Args a) {
;     ...
;             const int first = (rem == 0 ? bid : bid - rem) * 8 + wave, step = (rem == 0 ? G : G - rem) * 8;
;             {
;                 const int gt2 = (rem == 0 ? bid : bid - rem) * 512 + tid, ngt2 = (rem == 0 ? G : G - rem) * 512;
;                 for (int i = gt2; i < T * 64; i += ngt2) { const f32x4 v = ((const f32x4*)INF(I_P))[i]; u32x2 w; w.x = pk2(v[0], v[1]); w.y = pk2(v[2], v[3]); ((u32x2*)PB)[i] = w; }
;             }
;             for (int it = first; it < IT_REST; it += step) {
;                 int r = it;
;                 if (r < IT_DN) { const int kb = r / 64, nb = r % 64; transpose_item(INF(I_WDN), DM, WDN, DFF, 32 * nb, 64 * kb, 64 * kb, 32 * nb, scr, lane); continue; } r -= IT_DN;
;                 if (r < IT_SQ) { const int kb = r / 64, nb = r % 64; transpose_item(INF(I_WOUT), DM, WOUT, 2048, 32 * nb, 64 * kb, 64 * kb, 32 * nb, scr, lane); continue; } r -= IT_SQ;
;                 if (r < IT_SQ) { const int kb = r / 64, nb = r % 64; transpose_item(INF(I_WPG), DM, WPG, 2048, 32 * nb, 64 * kb, 64 * kb, 32 * nb, scr, lane); continue; } r -= IT_SQ;
;                 if (r < IT_BR) { const int kb = r / 64, nb = r % 64; transpose_item(INF(I_WATT), DM, WMRG, 2048, 32 * nb, 64 * kb, 64 * kb, 32 * nb, scr, lane); continue; } r -= IT_BR;
;                 if (r < IT_BR) { const int kb = r / 64, nb = r % 64; transpose_item(INF(I_WHGRN), DM, WMRG, 2048, 32 * nb, 1024 + 64 * kb, 64 * kb, 32 * nb, scr, lane); continue; } r -= IT_BR;
;                 { const int kb = r / 64, nb = r % 64; transpose_item(INF(I_WPP), DM, WPP, 256, 32 * nb, 64 * kb, 64 * kb, 32 * nb, scr, lane); }
;             }
.LBB0_136:
	s_or_b64 exec, exec, s[0:1]
	s_ashr_i32 s0, s3, 6
	s_lshl_b32 s1, s2, 3
	s_add_i32 s2, s0, s1
	s_add_i32 s2, s2, s94
	s_cmp_ge_i32 s2, s95
	s_cbranch_scc1 .LBB0_171
	v_lshlrev_b32_e32 v1, 3, v8
	s_lshl_b32 s0, s0, 14
	v_bfe_u32 v5, v8, 3, 3
	v_and_b32_e32 v16, 56, v1
	s_add_i32 s0, s0, 0
	v_bfe_u32 v0, v8, 5, 1
	v_and_b32_e32 v18, 31, v8
	v_mov_b32_e32 v3, 0
	v_mul_u32_u24_e32 v1, 0x84, v16
	v_lshlrev_b32_e32 v2, 1, v16
	v_lshlrev_b32_e32 v8, 2, v5
	s_mov_b32 s3, 0
	s_lshl_b32 s8, s12, 3
	v_lshl_add_u32 v4, v18, 2, s0
	s_movk_i32 s9, 0x84
	v_lshl_add_u64 v[6:7], s[62:63], 0, v[2:3]
	v_add3_u32 v20, s0, v1, v8
	v_or_b32_e32 v21, 8, v5
	v_or_b32_e32 v22, 16, v5
	v_or_b32_e32 v23, 24, v5
	v_lshl_add_u64 v[8:9], s[70:71], 0, v[2:3]
	v_lshl_add_u64 v[10:11], s[60:61], 0, v[2:3]
	v_lshl_add_u64 v[12:13], s[68:69], 0, v[2:3]
	v_lshl_add_u64 v[14:15], s[66:67], 0, v[2:3]
	v_mov_b32_e32 v1, v0
	s_add_i32 s10, 0, 0x23cd0
	s_add_i32 s11, 0, 0x23c88
	v_lshlrev_b32_e32 v16, 1, v16
	s_mov_b64 s[0:1], 0xfb400
	s_add_i32 s12, 0, 0x23c80
	s_add_i32 s13, 0, 0x23cc8
	s_add_i32 s14, 0, 0x23c90
	s_add_i32 s15, 0, 0x23cb0
	s_movk_i32 s16, 0x1600
	v_lshlrev_b32_e32 v2, 2, v18
	s_branch .LBB0_139
.LBB0_138:
	s_add_i32 s2, s2, s8
	s_cmp_lt_i32 s2, s95
	s_cbranch_scc0 .LBB0_171
